# v2 plus NA: bias/mask LDS reads batched 4 at a time with cndmask instead of exec branches, pass-1 K-fragment LDS reads pipelined via spare VGPRs, RPB/MT table copies batched
# speedup vs baseline: 1.0044x; 1.0044x over previous
; #define LAS __attribute__((address_space(3)))
; __device__ __forceinline__ void fourier_stage_c_block(LAS unsigned char* lds, rsrc_t R, int l, int bx, int G, int tid, int lane, int wave) {
;     ...
;         if (g != g_lds) {
;             const unsigned mb = OFF_MT + (unsigned)((l * 4 + g) * 128 * 256) * 2u;
; #pragma unroll
;             for (int i = 0; i < 8; ++i) { const u32x4 mv = bld<u32x4>(R, fo, mb + (unsigned)i * 8192u); *(LAS u32x4*)(lds + MT_LDS + i * 8192 + tid * 16) = mv; }
;             g_lds = g;
;         }
.LBB0_169:
	s_bfe_u32 s7, s11, 0x20006
	s_cmp_eq_u32 s7, s6
	s_cbranch_scc1 .LBB0_171
	s_lshl_b32 s0, s7, 16
	s_add_i32 s0, s3, s0
	s_mov_b32 s92, s34
	v_add_u32_e32 v84, 0, v208
	v_add_u32_e32 v84, 0x12000, v84
	s_mov_b32 s6, s7
	buffer_load_dwordx4 v[88:91], v208, s[92:95], s0 offen
	s_or_b32 s1, s0, 0x2000
	buffer_load_dwordx4 v[92:95], v208, s[92:95], s1 offen
	s_or_b32 s1, s0, 0x4000
	buffer_load_dwordx4 v[96:99], v208, s[92:95], s1 offen
	s_or_b32 s1, s0, 0x6000
	buffer_load_dwordx4 v[100:103], v208, s[92:95], s1 offen
	s_or_b32 s1, s0, 0x8000
	buffer_load_dwordx4 v[104:107], v208, s[92:95], s1 offen
	s_or_b32 s1, s0, 0xa000
	buffer_load_dwordx4 v[108:111], v208, s[92:95], s1 offen
	s_or_b32 s1, s0, 0xc000
	buffer_load_dwordx4 v[112:115], v208, s[92:95], s1 offen
	s_or_b32 s1, s0, 0xe000
	buffer_load_dwordx4 v[116:119], v208, s[92:95], s1 offen
	s_waitcnt vmcnt(0)
	ds_write_b128 v84, v[88:91]
	ds_write_b128 v84, v[92:95] offset:8192
	ds_write_b128 v84, v[96:99] offset:16384
	ds_write_b128 v84, v[100:103] offset:24576
	ds_write_b128 v84, v[104:107] offset:32768
	ds_write_b128 v84, v[108:111] offset:40960
	ds_write_b128 v84, v[112:115] offset:49152
	ds_write_b128 v84, v[116:119] offset:57344

; #define LAS __attribute__((address_space(3)))
; __device__ __forceinline__ void na_attn_block(LAS unsigned char* lds, rsrc_t R, int l, int bx, int G, int tid, int lane, int wave) {
;     ...
;     for (int i = tid; i < 8 * 15 * 31; i += NWAVES * 64) *(LAS float*)(lds + NA_RPB + i * 4) = bld<float>(R, (unsigned)i * 4u, OFF_RPB + (unsigned)(l * 8 * 15 * 31) * 4u);
.LBB0_181:
	s_mov_b32 s92, s34
	buffer_load_dword v2, v1, s[92:95], s4 offen
	buffer_load_dword v3, v1, s[92:95], s4 offen offset:2048
	s_add_i32 s6, s4, 0x1000
	buffer_load_dword v4, v1, s[92:95], s6 offen
	buffer_load_dword v5, v1, s[92:95], s6 offen offset:2048
	s_add_i32 s6, s4, 0x2000
	buffer_load_dword v6, v1, s[92:95], s6 offen
	buffer_load_dword v7, v1, s[92:95], s6 offen offset:2048
	s_add_i32 s6, s4, 0x3000
	buffer_load_dword v8, v1, s[92:95], s6 offen
	buffer_load_dword v9, v1, s[92:95], s6 offen offset:2048
	v_add_u32_e32 v1, 0x11000, v1
	s_movk_i32 s6, 0x88
	v_cmp_gt_u32_e32 vcc, s6, v162
	s_waitcnt vmcnt(0)
	ds_write_b32 v1, v2
	ds_write_b32 v1, v3 offset:2048
	ds_write_b32 v1, v4 offset:4096
	ds_write_b32 v1, v5 offset:6144
	ds_write_b32 v1, v6 offset:8192
	ds_write_b32 v1, v7 offset:10240
	ds_write_b32 v1, v8 offset:12288
	s_and_b64 exec, exec, vcc
	ds_write_b32 v1, v9 offset:14336

; __device__ __forceinline__ float sum_fq(float v) { v += __shfl_xor(v, 16); v += __shfl_xor(v, 32); return v; }
; #define LAS __attribute__((address_space(3)))
; #define SCHED_FENCE() __builtin_amdgcn_sched_barrier(0)
; #define NA_ISSUE(seq_, slot_) do { _Pragma("unroll") for (int j = 0; j < 4; ++j) st[slot_][j] = bld<u32x4>(R, co, ((seq_) < 8 ? (unsigned)WS_KB + rowb + (unsigned)((seq_) * 131072) : OFF_VT + rowb + (unsigned)(((seq_) - 8) * 131072)) + (unsigned)j * 8192u); } while (0)
; __device__ __forceinline__ void na_attn_block(LAS unsigned char* lds, rsrc_t R, int l, int bx, int G, int tid, int lane, int wave) {
;     ...
;         const int hp = u & 3, r = (u >> 2) & 127, b = u >> 9, h = 2 * hp + hsel;
;         int start = r - 4; start = start < 0 ? 0 : (start > 120 ? 120 : start);
;         const unsigned rowb = (unsigned)(((b * 128 + start) * 8 + 2 * hp) * 16384);
;         u32x4 st[3][4];
;     ...
;         u32x4 qraw[4]; float s0, s1;
;         { const unsigned q_off = OFF_PROJ + (unsigned)((b * SEQ + r * 64 + 16 * qg) * PROJ_W + h * HD) * 2u;
; #pragma unroll
;           for (int ks = 0; ks < 4; ++ks) qraw[ks] = bld<u32x4>(R, qo, q_off + 64 * ks);
;           const int hs = wave & 1, a0 = wave >> 1;
;           const unsigned sso = OFF_SS + (unsigned)(SS_H + (size_t)(l * 20 + 2 * hp + hs) * NTOK + b * SEQ + (start + a0) * 64) * 4u;
;           s0 = bld<float>(R, (unsigned)(lane * 4), sso); s1 = bld<float>(R, (unsigned)(lane * 4), sso + 4u * 64u * 4u); }
;         SCHED_FENCE();
;         NA_ISSUE(0, 0); NA_ISSUE(1, 1); NA_ISSUE(2, 2);
;         SCHED_FENCE();
;         *(LAS float*)(lds + NA_SSK + tid * 4) = __builtin_amdgcn_rsqf(s0 * (1.f / HD) + EPS); *(LAS float*)(lds + NA_SSK + (tid + 512) * 4) = __builtin_amdgcn_rsqf(s1 * (1.f / HD) + EPS);
;         bf16x8 qf[4];
;         { float qv[4][8]; float ss = 0.f;
; #pragma unroll
;           for (int ks = 0; ks < 4; ++ks)
; #pragma unroll
;               for (int j = 0; j < 4; ++j) { const unsigned w = qraw[ks][j]; qv[ks][2 * j] = __builtin_bit_cast(float, w << 16); qv[ks][2 * j + 1] = __builtin_bit_cast(float, w & 0xffff0000u); ss += qv[ks][2 * j] * qv[ks][2 * j] + qv[ks][2 * j + 1] * qv[ks][2 * j + 1]; }
;           ss = pg8::sum_fq(ss);
.LBB0_185:
	s_bfe_u32 s2, s11, 0x70002
	v_med3_u32 v250, s2, 4, v222
	s_ashr_i32 s16, s11, 9
	v_readfirstlane_b32 s15, v250
	s_add_i32 s15, s15, -4
	s_lshl_b32 s12, s16, 10
	s_lshl_b32 s13, s15, 3
	s_and_b32 s17, s10, 6
	s_add_i32 s13, s13, s12
	s_or_b32 s14, s13, s17
	s_lshl_b32 s12, s16, 13
	s_lshl_b32 s13, s2, 6
	v_readlane_b32 s3, v253, 32
	s_or_b32 s12, s13, s12
	v_readlane_b32 s13, v253, 30
	s_add_i32 s3, s17, s3
	s_or_b32 s12, s12, s13
	s_lshl_b32 s13, s3, 8
	s_mul_i32 s18, s12, 0x1800
	s_add_i32 s18, s13, s18
	s_add_i32 s18, s18, 0x14e00000
	s_or_b32 s19, s18, 64
	buffer_load_dwordx4 v[64:67], v232, s[40:43], s18 offen
	buffer_load_dwordx4 v[68:71], v232, s[40:43], s19 offen
	s_or_b32 s19, s18, 0x80
	s_or_b32 s18, s18, 0xc0
	buffer_load_dwordx4 v[84:87], v232, s[40:43], s19 offen
	buffer_load_dwordx4 v[92:95], v232, s[40:43], s18 offen
	s_add_i32 s17, s4, s17
	v_readlane_b32 s18, v253, 37
	s_add_i32 s18, s15, s18
	s_lshl_b32 s17, s17, 17
	s_lshl_b32 s16, s16, 15
	s_lshl_b32 s18, s18, 8
	s_add_i32 s16, s16, s17
	s_add_i32 s16, s16, s18
	s_add_i32 s17, s16, 0x1a0000
	s_add_i32 s16, s16, 0x1a0400
	buffer_load_dword v96, v234, s[40:43], s17 offen
	buffer_load_dword v97, v234, s[40:43], s16 offen
	s_lshl_b32 s14, s14, 14
	s_add_i32 s16, s14, 0x30e00000
	buffer_load_dwordx4 v[72:75], v208, s[40:43], s16 offen
	s_add_i32 s16, s14, 0x30e02000
	buffer_load_dwordx4 v[76:79], v208, s[40:43], s16 offen
	s_add_i32 s16, s14, 0x30e04000
	buffer_load_dwordx4 v[80:83], v208, s[40:43], s16 offen
	s_add_i32 s16, s14, 0x30e06000
	buffer_load_dwordx4 v[88:91], v208, s[40:43], s16 offen
	s_add_i32 s16, s14, 0x30e20000
	buffer_load_dwordx4 v[48:51], v208, s[40:43], s16 offen
	s_add_i32 s16, s14, 0x30e22000
	buffer_load_dwordx4 v[52:55], v208, s[40:43], s16 offen
	s_add_i32 s16, s14, 0x30e24000
	buffer_load_dwordx4 v[56:59], v208, s[40:43], s16 offen
	s_add_i32 s16, s14, 0x30e26000
	buffer_load_dwordx4 v[60:63], v208, s[40:43], s16 offen
	s_add_i32 s16, s14, 0x30e40000
	buffer_load_dwordx4 v[32:35], v208, s[40:43], s16 offen
	s_add_i32 s16, s14, 0x30e42000
	buffer_load_dwordx4 v[36:39], v208, s[40:43], s16 offen
	s_add_i32 s16, s14, 0x30e44000
	buffer_load_dwordx4 v[40:43], v208, s[40:43], s16 offen
	s_add_i32 s16, s14, 0x30e46000
	buffer_load_dwordx4 v[44:47], v208, s[40:43], s16 offen
	s_waitcnt vmcnt(0)
	v_and_b32_e32 v101, 0xffff0000, v64
	v_and_b32_e32 v103, 0xffff0000, v65
	v_lshlrev_b32_e32 v100, 16, v64
	v_mul_f32_e32 v64, v101, v101
	v_lshlrev_b32_e32 v102, 16, v65
	v_mul_f32_e32 v65, v103, v103
	v_fmac_f32_e32 v64, v100, v100
	v_fmac_f32_e32 v65, v102, v102
	v_lshlrev_b32_e32 v104, 16, v66
	v_and_b32_e32 v66, 0xffff0000, v66
	v_add_f32_e32 v64, v64, v65
	v_mul_f32_e32 v65, v66, v66
	v_fmac_f32_e32 v65, v104, v104
	v_lshlrev_b32_e32 v105, 16, v67
	v_and_b32_e32 v67, 0xffff0000, v67
	v_add_f32_e32 v64, v65, v64
	v_mul_f32_e32 v65, v67, v67
	v_fmac_f32_e32 v65, v105, v105
	v_lshlrev_b32_e32 v106, 16, v68
	v_and_b32_e32 v68, 0xffff0000, v68
	v_add_f32_e32 v64, v65, v64
	v_mul_f32_e32 v65, v68, v68
	v_fmac_f32_e32 v65, v106, v106
	v_lshlrev_b32_e32 v107, 16, v69
	v_and_b32_e32 v69, 0xffff0000, v69
	v_add_f32_e32 v64, v65, v64
	v_mul_f32_e32 v65, v69, v69
	v_fmac_f32_e32 v65, v107, v107
	v_lshlrev_b32_e32 v108, 16, v70
	v_and_b32_e32 v70, 0xffff0000, v70
	v_add_f32_e32 v64, v65, v64
	v_mul_f32_e32 v65, v70, v70
	v_fmac_f32_e32 v65, v108, v108
	v_lshlrev_b32_e32 v109, 16, v71
	v_and_b32_e32 v71, 0xffff0000, v71
	v_add_f32_e32 v64, v65, v64
	v_mul_f32_e32 v65, v71, v71
	v_fmac_f32_e32 v65, v109, v109
	v_and_b32_e32 v111, 0xffff0000, v84
	v_add_f32_e32 v64, v65, v64
	v_lshlrev_b32_e32 v110, 16, v84
	v_mul_f32_e32 v65, v111, v111
	v_fmac_f32_e32 v65, v110, v110
	v_and_b32_e32 v113, 0xffff0000, v85
	v_fmamk_f32 v96, v96, 0x3c000000, v218
	v_fmamk_f32 v97, v97, 0x3c000000, v218
	v_add_f32_e32 v64, v65, v64
	v_lshlrev_b32_e32 v112, 16, v85
	v_mul_f32_e32 v65, v113, v113
	v_rsq_f32_e32 v96, v96
	v_rsq_f32_e32 v97, v97
	v_fmac_f32_e32 v65, v112, v112
	v_and_b32_e32 v115, 0xffff0000, v86
	v_add_f32_e32 v64, v65, v64
	v_lshlrev_b32_e32 v114, 16, v86
	v_mul_f32_e32 v65, v115, v115
	v_fmac_f32_e32 v65, v114, v114
	v_and_b32_e32 v117, 0xffff0000, v87
	v_add_f32_e32 v64, v65, v64
	v_lshlrev_b32_e32 v116, 16, v87
	v_mul_f32_e32 v65, v117, v117
	ds_write2st64_b32 v246, v96, v97 offset1:8
	v_fmac_f32_e32 v65, v116, v116
	v_lshlrev_b32_e32 v97, 16, v93
	v_lshlrev_b32_e32 v96, 16, v92
	v_and_b32_e32 v93, 0xffff0000, v93
	v_and_b32_e32 v92, 0xffff0000, v92
	v_add_f32_e32 v84, v65, v64
	v_pk_mul_f32 v[64:65], v[92:93], v[92:93]
	v_lshlrev_b32_e32 v99, 16, v95
	v_pk_fma_f32 v[64:65], v[96:97], v[96:97], v[64:65]
	v_lshlrev_b32_e32 v98, 16, v94
	v_add_f32_e32 v64, v64, v84
	v_and_b32_e32 v95, 0xffff0000, v95
	v_and_b32_e32 v94, 0xffff0000, v94
	v_add_f32_e32 v84, v65, v64
	v_pk_mul_f32 v[64:65], v[94:95], v[94:95]
	v_add_u32_e32 v249, 0, v208
	v_pk_fma_f32 v[64:65], v[98:99], v[98:99], v[64:65]
	s_add_i32 s16, s14, 0x30e60000
	v_add_f32_e32 v64, v64, v84
	v_add_f32_e32 v64, v65, v64
	ds_bpermute_b32 v65, v235, v64
	s_waitcnt lgkmcnt(0)
	v_add_f32_e32 v64, v64, v65
	ds_bpermute_b32 v65, v236, v64
	s_waitcnt lgkmcnt(0)
; __device__ __forceinline__ unsigned cvt_pk_bf16(float lo, float hi) { unsigned r; asm volatile("v_cvt_pk_bf16_f32 %0, %1, %2" : "=v"(r) : "v"(lo), "v"(hi)); return r; }
; #define LAS __attribute__((address_space(3)))
; #define MFMA16(a, b, c) __builtin_amdgcn_mfma_f32_16x16x32_bf16((a), (b), (c), 0, 0, 0)
; #define SCHED_FENCE() __builtin_amdgcn_sched_barrier(0)
; #define NA_ISSUE(seq_, slot_) do { _Pragma("unroll") for (int j = 0; j < 4; ++j) st[slot_][j] = bld<u32x4>(R, co, ((seq_) < 8 ? (unsigned)WS_KB + rowb + (unsigned)((seq_) * 131072) : OFF_VT + rowb + (unsigned)(((seq_) - 8) * 131072)) + (unsigned)j * 8192u); } while (0)
; #define NA_WRITE(slot_, buf_) do { _Pragma("unroll") for (int j = 0; j < 4; ++j) *(LAS u32x4*)(lds + (buf_) * NA_BUF + j * 8192 + tid * 16) = st[slot_][j]; } while (0)
; __device__ __forceinline__ void na_attn_block(LAS unsigned char* lds, rsrc_t R, int l, int bx, int G, int tid, int lane, int wave) {
;     ...
;           const float rq = __builtin_amdgcn_rsqf(ss * (1.f / HD) + EPS);
; #pragma unroll
;           for (int ks = 0; ks < 4; ++ks) { const f32x4 g0 = gq[ks][0], g1 = gq[ks][1];
;               u32x4 w; w.x = pg8::cvt_pk_bf16(qv[ks][0] * rq * g0[0], qv[ks][1] * rq * g0[1]); w.y = pg8::cvt_pk_bf16(qv[ks][2] * rq * g0[2], qv[ks][3] * rq * g0[3]);
;               w.z = pg8::cvt_pk_bf16(qv[ks][4] * rq * g1[0], qv[ks][5] * rq * g1[1]); w.w = pg8::cvt_pk_bf16(qv[ks][6] * rq * g1[2], qv[ks][7] * rq * g1[3]);
;               qf[ks] = __builtin_bit_cast(bf16x8, w); } }
;         NA_WRITE(0, 0);
;         __syncthreads();
;         f32x4 S[8][2];
; #pragma unroll
;         for (int a = 0; a < 8; ++a) {
;             NA_ISSUE(a + 3, a % 3);
;             SCHED_FENCE();
;             const int buf = (a & 1) * NA_BUF;
; #pragma unroll
;             for (int t = 0; t < 2; ++t) {
;                 f32x4 acc = (f32x4){0.f, 0.f, 0.f, 0.f};
; #pragma unroll
;                 for (int ks = 0; ks < 4; ++ks) { const bf16x8 kf = *(const LAS bf16x8*)(lds + kfb + buf + t * 4096 + ks * 512); acc = MFMA16(kf, qf[ks], acc); }
;                 const f32x4 rk = *(const LAS f32x4*)(lds + skb + a * 512 + t * 64);
;                 S[a][t] = acc * rk;
;             }
	v_add_f32_e32 v64, v64, v65
	v_fmamk_f32 v64, v64, 0x3c000000, v218
	v_rsq_f32_e32 v118, v64
	s_nop 0
	v_mul_f32_e32 v64, v118, v100
	v_mul_f32_e32 v65, v118, v101
	v_mul_f32_e32 v64, v28, v64
	v_mul_f32_e32 v65, v29, v65
	v_cvt_pk_bf16_f32 v84, v64, v65
	v_mul_f32_e32 v64, v118, v102
	v_mul_f32_e32 v65, v118, v103
	v_mul_f32_e32 v64, v30, v64
	v_mul_f32_e32 v65, v31, v65
	v_cvt_pk_bf16_f32 v85, v64, v65
	v_mul_f32_e32 v64, v118, v104
	v_mul_f32_e32 v65, v118, v66
	v_mul_f32_e32 v64, v24, v64
	v_mul_f32_e32 v65, v25, v65
	v_cvt_pk_bf16_f32 v86, v64, v65
	v_mul_f32_e32 v64, v118, v105
	v_mul_f32_e32 v65, v118, v67
	v_mul_f32_e32 v64, v26, v64
	v_mul_f32_e32 v65, v27, v65
	v_cvt_pk_bf16_f32 v87, v64, v65
	v_mul_f32_e32 v64, v118, v106
	v_mul_f32_e32 v65, v118, v68
	v_mul_f32_e32 v64, v20, v64
	v_mul_f32_e32 v65, v21, v65
	v_cvt_pk_bf16_f32 v64, v64, v65
	v_mul_f32_e32 v65, v118, v107
	v_mul_f32_e32 v66, v118, v69
	v_mul_f32_e32 v65, v22, v65
	v_mul_f32_e32 v66, v23, v66
	v_cvt_pk_bf16_f32 v65, v65, v66
	v_mul_f32_e32 v66, v118, v108
	v_mul_f32_e32 v67, v118, v70
	v_mul_f32_e32 v66, v16, v66
	v_mul_f32_e32 v67, v17, v67
	v_cvt_pk_bf16_f32 v66, v66, v67
	v_mul_f32_e32 v67, v118, v109
	v_mul_f32_e32 v68, v118, v71
	v_mul_f32_e32 v67, v18, v67
	v_mul_f32_e32 v68, v19, v68
	v_cvt_pk_bf16_f32 v67, v67, v68
	v_mul_f32_e32 v68, v118, v110
	v_mul_f32_e32 v69, v118, v111
	v_mul_f32_e32 v68, v12, v68
	v_mul_f32_e32 v69, v13, v69
	v_cvt_pk_bf16_f32 v68, v68, v69
	v_mul_f32_e32 v69, v118, v112
	v_mul_f32_e32 v70, v118, v113
	v_mul_f32_e32 v69, v14, v69
	v_mul_f32_e32 v70, v15, v70
	v_cvt_pk_bf16_f32 v69, v69, v70
	v_mul_f32_e32 v70, v118, v114
	v_mul_f32_e32 v71, v118, v115
	v_mul_f32_e32 v70, v8, v70
	v_mul_f32_e32 v71, v9, v71
	v_cvt_pk_bf16_f32 v70, v70, v71
	v_mul_f32_e32 v71, v118, v116
	v_mul_f32_e32 v92, v118, v92
	v_mul_f32_e32 v71, v10, v71
	v_mul_f32_e32 v100, v118, v117
	v_mul_f32_e32 v96, v118, v96
	v_mul_f32_e32 v92, v5, v92
	v_mul_f32_e32 v100, v11, v100
	v_cvt_pk_bf16_f32 v71, v71, v100
	v_mul_f32_e32 v96, v4, v96
	v_cvt_pk_bf16_f32 v104, v96, v92
	v_mul_f32_e32 v92, v118, v97
	v_mul_f32_e32 v93, v118, v93
	v_mul_f32_e32 v92, v6, v92
	v_mul_f32_e32 v93, v7, v93
	v_cvt_pk_bf16_f32 v105, v92, v93
	v_mul_f32_e32 v92, v118, v98
	v_mul_f32_e32 v93, v118, v94
	v_mul_f32_e32 v92, v0, v92
	v_mul_f32_e32 v93, v1, v93
	v_cvt_pk_bf16_f32 v106, v92, v93
	v_mul_f32_e32 v92, v118, v99
	v_mul_f32_e32 v93, v118, v95
	v_mul_f32_e32 v92, v2, v92
	v_mul_f32_e32 v93, v3, v93
	v_cvt_pk_bf16_f32 v107, v92, v93
	ds_write_b128 v249, v[72:75]
	ds_write_b128 v249, v[76:79] offset:8192
	ds_write_b128 v249, v[80:83] offset:16384
	ds_write_b128 v249, v[88:91] offset:24576
	s_waitcnt lgkmcnt(0)
	s_barrier
	buffer_load_dwordx4 v[72:75], v208, s[40:43], s16 offen
	s_add_i32 s16, s14, 0x30e62000
	buffer_load_dwordx4 v[76:79], v208, s[40:43], s16 offen
	s_add_i32 s16, s14, 0x30e64000
	buffer_load_dwordx4 v[80:83], v208, s[40:43], s16 offen
	s_add_i32 s16, s14, 0x30e66000
	buffer_load_dwordx4 v[88:91], v208, s[40:43], s16 offen
	s_nop 7
	ds_read_b128 v[210:213], v247
	ds_read_b128 v[224:227], v247 offset:512
	ds_read_b128 v[184:187], v248 offset:64
	ds_read_b128 v[228:231], v247 offset:1024
	ds_read_b128 v[96:99], v248
	s_waitcnt lgkmcnt(4)
	v_mfma_f32_16x16x32_bf16 v[92:95], v[210:213], v[84:87], 0
	ds_read_b128 v[210:213], v247 offset:1536
	s_waitcnt lgkmcnt(4)
	v_mfma_f32_16x16x32_bf16 v[92:95], v[224:227], v[64:67], v[92:95]
	ds_read_b128 v[224:227], v247 offset:4096
	s_waitcnt lgkmcnt(3)
	v_mfma_f32_16x16x32_bf16 v[92:95], v[228:231], v[68:71], v[92:95]
	ds_read_b128 v[228:231], v247 offset:4608
	s_waitcnt lgkmcnt(2)
	v_mfma_f32_16x16x32_bf16 v[92:95], v[210:213], v[104:107], v[92:95]
	ds_read_b128 v[210:213], v247 offset:5120
	s_nop 6
	v_pk_mul_f32 v[214:215], v[94:95], v[98:99]
	v_pk_mul_f32 v[216:217], v[92:93], v[96:97]
	s_waitcnt lgkmcnt(2)
	v_mfma_f32_16x16x32_bf16 v[92:95], v[224:227], v[84:87], 0
	ds_read_b128 v[224:227], v247 offset:5632
	s_waitcnt lgkmcnt(2)
	v_mfma_f32_16x16x32_bf16 v[92:95], v[228:231], v[64:67], v[92:95]
	s_waitcnt lgkmcnt(1)
	v_mfma_f32_16x16x32_bf16 v[92:95], v[210:213], v[68:71], v[92:95]
	s_waitcnt lgkmcnt(0)
	v_mfma_f32_16x16x32_bf16 v[176:179], v[224:227], v[104:107], v[92:95]
	s_nop 7
	s_nop 0
	s_add_i32 s16, s14, 0x30e80000
	ds_write_b128 v249, v[48:51] offset:32768
	ds_write_b128 v249, v[52:55] offset:40960
	ds_write_b128 v249, v[56:59] offset:49152
	ds_write_b128 v249, v[60:63] offset:57344
	s_waitcnt lgkmcnt(0)
	s_barrier
	buffer_load_dwordx4 v[48:51], v208, s[40:43], s16 offen
	s_add_i32 s16, s14, 0x30e82000
	buffer_load_dwordx4 v[52:55], v208, s[40:43], s16 offen
	s_add_i32 s16, s14, 0x30e84000
	buffer_load_dwordx4 v[56:59], v208, s[40:43], s16 offen
	s_add_i32 s16, s14, 0x30e86000
	buffer_load_dwordx4 v[92:95], v208, s[40:43], s16 offen
	s_nop 7
	ds_read_b128 v[210:213], v247 offset:32768
	ds_read_b128 v[224:227], v247 offset:33280
	ds_read_b128 v[228:231], v247 offset:33792
	ds_read_b128 v[168:171], v248 offset:512
	ds_read_b128 v[180:183], v248 offset:576
	s_waitcnt lgkmcnt(4)
	v_mfma_f32_16x16x32_bf16 v[60:63], v[210:213], v[84:87], 0
	ds_read_b128 v[210:213], v247 offset:34304
	s_waitcnt lgkmcnt(4)
	v_mfma_f32_16x16x32_bf16 v[60:63], v[224:227], v[64:67], v[60:63]
	ds_read_b128 v[224:227], v247 offset:36864
	s_waitcnt lgkmcnt(4)
	v_mfma_f32_16x16x32_bf16 v[60:63], v[228:231], v[68:71], v[60:63]
	ds_read_b128 v[228:231], v247 offset:37376
	s_waitcnt lgkmcnt(2)
	v_mfma_f32_16x16x32_bf16 v[164:167], v[210:213], v[104:107], v[60:63]
	ds_read_b128 v[210:213], v247 offset:37888
	s_waitcnt lgkmcnt(2)
	v_mfma_f32_16x16x32_bf16 v[60:63], v[224:227], v[84:87], 0
	ds_read_b128 v[224:227], v247 offset:38400
	s_waitcnt lgkmcnt(2)
	v_mfma_f32_16x16x32_bf16 v[60:63], v[228:231], v[64:67], v[60:63]
	s_waitcnt lgkmcnt(1)
	v_mfma_f32_16x16x32_bf16 v[60:63], v[210:213], v[68:71], v[60:63]
	s_waitcnt lgkmcnt(0)
	v_mfma_f32_16x16x32_bf16 v[172:175], v[224:227], v[104:107], v[60:63]
	s_nop 7
	s_nop 0
	s_add_i32 s16, s14, 0x30ea0000
	ds_write_b128 v249, v[32:35]
	ds_write_b128 v249, v[36:39] offset:8192
	ds_write_b128 v249, v[40:43] offset:16384
	ds_write_b128 v249, v[44:47] offset:24576
	s_waitcnt lgkmcnt(0)
	s_barrier
; #define LAS __attribute__((address_space(3)))
; #define MFMA16(a, b, c) __builtin_amdgcn_mfma_f32_16x16x32_bf16((a), (b), (c), 0, 0, 0)
; #define SCHED_FENCE() __builtin_amdgcn_sched_barrier(0)
; #define NA_ISSUE(seq_, slot_) do { _Pragma("unroll") for (int j = 0; j < 4; ++j) st[slot_][j] = bld<u32x4>(R, co, ((seq_) < 8 ? (unsigned)WS_KB + rowb + (unsigned)((seq_) * 131072) : OFF_VT + rowb + (unsigned)(((seq_) - 8) * 131072)) + (unsigned)j * 8192u); } while (0)
; #define NA_WRITE(slot_, buf_) do { _Pragma("unroll") for (int j = 0; j < 4; ++j) *(LAS u32x4*)(lds + (buf_) * NA_BUF + j * 8192 + tid * 16) = st[slot_][j]; } while (0)
; __device__ __forceinline__ void na_attn_block(LAS unsigned char* lds, rsrc_t R, int l, int bx, int G, int tid, int lane, int wave) {
;     ...
;         for (int a = 0; a < 8; ++a) {
;             NA_ISSUE(a + 3, a % 3);
;             SCHED_FENCE();
;             const int buf = (a & 1) * NA_BUF;
; #pragma unroll
;             for (int t = 0; t < 2; ++t) {
;                 f32x4 acc = (f32x4){0.f, 0.f, 0.f, 0.f};
; #pragma unroll
;                 for (int ks = 0; ks < 4; ++ks) { const bf16x8 kf = *(const LAS bf16x8*)(lds + kfb + buf + t * 4096 + ks * 512); acc = MFMA16(kf, qf[ks], acc); }
;                 const f32x4 rk = *(const LAS f32x4*)(lds + skb + a * 512 + t * 64);
;                 S[a][t] = acc * rk;
;             }
;             SCHED_FENCE();
;             NA_WRITE((a + 1) % 3, (a + 1) & 1);
;             __syncthreads();
	buffer_load_dwordx4 v[32:35], v208, s[40:43], s16 offen
	s_add_i32 s16, s14, 0x30ea2000
	buffer_load_dwordx4 v[40:43], v208, s[40:43], s16 offen
	s_add_i32 s16, s14, 0x30ea4000
	buffer_load_dwordx4 v[60:63], v208, s[40:43], s16 offen
	s_add_i32 s16, s14, 0x30ea6000
	buffer_load_dwordx4 v[96:99], v208, s[40:43], s16 offen
	s_nop 7
	ds_read_b128 v[210:213], v247
	ds_read_b128 v[224:227], v247 offset:512
	ds_read_b128 v[228:231], v247 offset:1024
	ds_read_b128 v[152:155], v248 offset:1024
	ds_read_b128 v[160:163], v248 offset:1088
	s_waitcnt lgkmcnt(4)
	v_mfma_f32_16x16x32_bf16 v[36:39], v[210:213], v[84:87], 0
	ds_read_b128 v[210:213], v247 offset:1536
	s_waitcnt lgkmcnt(4)
	v_mfma_f32_16x16x32_bf16 v[36:39], v[224:227], v[64:67], v[36:39]
	ds_read_b128 v[224:227], v247 offset:4096
	s_waitcnt lgkmcnt(4)
	v_mfma_f32_16x16x32_bf16 v[36:39], v[228:231], v[68:71], v[36:39]
	ds_read_b128 v[228:231], v247 offset:4608
	s_waitcnt lgkmcnt(2)
	v_mfma_f32_16x16x32_bf16 v[148:151], v[210:213], v[104:107], v[36:39]
	ds_read_b128 v[210:213], v247 offset:5120
	s_waitcnt lgkmcnt(2)
	v_mfma_f32_16x16x32_bf16 v[36:39], v[224:227], v[84:87], 0
	ds_read_b128 v[224:227], v247 offset:5632
	s_waitcnt lgkmcnt(2)
	v_mfma_f32_16x16x32_bf16 v[36:39], v[228:231], v[64:67], v[36:39]
	s_waitcnt lgkmcnt(1)
	v_mfma_f32_16x16x32_bf16 v[36:39], v[210:213], v[68:71], v[36:39]
	s_waitcnt lgkmcnt(0)
	v_mfma_f32_16x16x32_bf16 v[156:159], v[224:227], v[104:107], v[36:39]
	s_nop 7
	s_nop 0
	s_add_i32 s16, s14, 0x30ec0000
	s_waitcnt vmcnt(11)
	ds_write_b128 v249, v[72:75] offset:32768
	s_waitcnt vmcnt(10)
	ds_write_b128 v249, v[76:79] offset:40960
	s_waitcnt vmcnt(9)
	ds_write_b128 v249, v[80:83] offset:49152
	s_waitcnt vmcnt(8)
	ds_write_b128 v249, v[88:91] offset:57344
	s_waitcnt lgkmcnt(0)
	s_barrier
	buffer_load_dwordx4 v[36:39], v208, s[40:43], s16 offen
	s_add_i32 s16, s14, 0x30ec2000
	buffer_load_dwordx4 v[44:47], v208, s[40:43], s16 offen
	s_add_i32 s16, s14, 0x30ec4000
	buffer_load_dwordx4 v[72:75], v208, s[40:43], s16 offen
	s_add_i32 s16, s14, 0x30ec6000
	buffer_load_dwordx4 v[76:79], v208, s[40:43], s16 offen
	s_nop 7
	ds_read_b128 v[210:213], v247 offset:32768
	ds_read_b128 v[224:227], v247 offset:33280
	ds_read_b128 v[228:231], v247 offset:33792
	ds_read_b128 v[132:135], v248 offset:1536
	ds_read_b128 v[144:147], v248 offset:1600
	s_waitcnt lgkmcnt(4)
	v_mfma_f32_16x16x32_bf16 v[80:83], v[210:213], v[84:87], 0
	ds_read_b128 v[210:213], v247 offset:34304
	s_waitcnt lgkmcnt(4)
	v_mfma_f32_16x16x32_bf16 v[80:83], v[224:227], v[64:67], v[80:83]
	ds_read_b128 v[224:227], v247 offset:36864
	s_waitcnt lgkmcnt(4)
	v_mfma_f32_16x16x32_bf16 v[80:83], v[228:231], v[68:71], v[80:83]
	ds_read_b128 v[228:231], v247 offset:37376
	s_waitcnt lgkmcnt(2)
	v_mfma_f32_16x16x32_bf16 v[128:131], v[210:213], v[104:107], v[80:83]
	ds_read_b128 v[210:213], v247 offset:37888
	s_waitcnt lgkmcnt(2)
	v_mfma_f32_16x16x32_bf16 v[80:83], v[224:227], v[84:87], 0
	ds_read_b128 v[224:227], v247 offset:38400
	s_waitcnt lgkmcnt(2)
	v_mfma_f32_16x16x32_bf16 v[80:83], v[228:231], v[64:67], v[80:83]
	s_waitcnt lgkmcnt(1)
	v_mfma_f32_16x16x32_bf16 v[80:83], v[210:213], v[68:71], v[80:83]
	s_waitcnt lgkmcnt(0)
	v_mfma_f32_16x16x32_bf16 v[136:139], v[224:227], v[104:107], v[80:83]
	s_nop 7
	s_nop 0
	s_add_i32 s16, s14, 0x30ee0000
	s_waitcnt vmcnt(11)
	ds_write_b128 v249, v[48:51]
	s_waitcnt vmcnt(10)
	ds_write_b128 v249, v[52:55] offset:8192
	s_waitcnt vmcnt(9)
	ds_write_b128 v249, v[56:59] offset:16384
	s_waitcnt vmcnt(8)
	ds_write_b128 v249, v[92:95] offset:24576
	s_waitcnt lgkmcnt(0)
	s_barrier
	buffer_load_dwordx4 v[48:51], v208, s[40:43], s16 offen
	s_add_i32 s16, s14, 0x30ee2000
	buffer_load_dwordx4 v[52:55], v208, s[40:43], s16 offen
	s_add_i32 s16, s14, 0x30ee4000
	buffer_load_dwordx4 v[140:143], v208, s[40:43], s16 offen
	s_add_i32 s16, s14, 0x30ee6000
	buffer_load_dwordx4 v[192:195], v208, s[40:43], s16 offen
	s_nop 7
	ds_read_b128 v[210:213], v247
	ds_read_b128 v[224:227], v247 offset:512
	ds_read_b128 v[228:231], v247 offset:1024
	ds_read_b128 v[120:123], v248 offset:2048
	ds_read_b128 v[124:127], v248 offset:2112
	s_waitcnt lgkmcnt(4)
	v_mfma_f32_16x16x32_bf16 v[56:59], v[210:213], v[84:87], 0
	ds_read_b128 v[210:213], v247 offset:1536
	s_waitcnt lgkmcnt(4)
	v_mfma_f32_16x16x32_bf16 v[56:59], v[224:227], v[64:67], v[56:59]
	ds_read_b128 v[224:227], v247 offset:4096
	s_waitcnt lgkmcnt(4)
	v_mfma_f32_16x16x32_bf16 v[56:59], v[228:231], v[68:71], v[56:59]
	ds_read_b128 v[228:231], v247 offset:4608
	s_waitcnt lgkmcnt(2)
	v_mfma_f32_16x16x32_bf16 v[116:119], v[210:213], v[104:107], v[56:59]
	ds_read_b128 v[210:213], v247 offset:5120
	s_waitcnt lgkmcnt(2)
	v_mfma_f32_16x16x32_bf16 v[56:59], v[224:227], v[84:87], 0
	ds_read_b128 v[224:227], v247 offset:5632
	s_waitcnt lgkmcnt(2)
	v_mfma_f32_16x16x32_bf16 v[56:59], v[228:231], v[64:67], v[56:59]
	s_waitcnt lgkmcnt(1)
	v_mfma_f32_16x16x32_bf16 v[56:59], v[210:213], v[68:71], v[56:59]
	s_waitcnt lgkmcnt(0)
	v_mfma_f32_16x16x32_bf16 v[112:115], v[224:227], v[104:107], v[56:59]
	s_nop 7
	s_nop 0
	s_add_i32 s16, s14, 0x20e00000
	s_waitcnt vmcnt(11)
	ds_write_b128 v249, v[32:35] offset:32768
	s_waitcnt vmcnt(10)
	ds_write_b128 v249, v[40:43] offset:40960
	s_waitcnt vmcnt(9)
	ds_write_b128 v249, v[60:63] offset:49152
	s_waitcnt vmcnt(8)
	ds_write_b128 v249, v[96:99] offset:57344
	s_waitcnt lgkmcnt(0)
	s_barrier
; #define LAS __attribute__((address_space(3)))
; #define MFMA16(a, b, c) __builtin_amdgcn_mfma_f32_16x16x32_bf16((a), (b), (c), 0, 0, 0)
; #define SCHED_FENCE() __builtin_amdgcn_sched_barrier(0)
; #define NA_ISSUE(seq_, slot_) do { _Pragma("unroll") for (int j = 0; j < 4; ++j) st[slot_][j] = bld<u32x4>(R, co, ((seq_) < 8 ? (unsigned)WS_KB + rowb + (unsigned)((seq_) * 131072) : OFF_VT + rowb + (unsigned)(((seq_) - 8) * 131072)) + (unsigned)j * 8192u); } while (0)
; #define NA_WRITE(slot_, buf_) do { _Pragma("unroll") for (int j = 0; j < 4; ++j) *(LAS u32x4*)(lds + (buf_) * NA_BUF + j * 8192 + tid * 16) = st[slot_][j]; } while (0)
; __device__ __forceinline__ void na_attn_block(LAS unsigned char* lds, rsrc_t R, int l, int bx, int G, int tid, int lane, int wave) {
;     ...
;         for (int a = 0; a < 8; ++a) {
;             NA_ISSUE(a + 3, a % 3);
;             SCHED_FENCE();
;             const int buf = (a & 1) * NA_BUF;
; #pragma unroll
;             for (int t = 0; t < 2; ++t) {
;                 f32x4 acc = (f32x4){0.f, 0.f, 0.f, 0.f};
; #pragma unroll
;                 for (int ks = 0; ks < 4; ++ks) { const bf16x8 kf = *(const LAS bf16x8*)(lds + kfb + buf + t * 4096 + ks * 512); acc = MFMA16(kf, qf[ks], acc); }
;                 const f32x4 rk = *(const LAS f32x4*)(lds + skb + a * 512 + t * 64);
;                 S[a][t] = acc * rk;
;             }
;             SCHED_FENCE();
;             NA_WRITE((a + 1) % 3, (a + 1) & 1);
;             __syncthreads();
;         }
;         { const int rowidx0 = start - r + 7;
; #pragma unroll
;           for (int a = 0; a < 8; ++a)
; #pragma unroll
;               for (int q = 0; q < 8; ++q) { const int kcol = kc0 + 16 * (q >> 2) + 4 * kq + (q & 3); const bool valid = (kcol >= cs) && (kcol < cs + 16);
;                   int ci = kcol - qcol + 15; ci = ci < 0 ? 0 : (ci > 30 ? 30 : ci);
;                   const float bias = *(const LAS float*)(lds + NA_RPB + ((h * 15 + rowidx0 + a) * 31 + ci) * 4);
	buffer_load_dwordx4 v[188:191], v208, s[40:43], s16 offen
	s_add_i32 s16, s14, 0x20e02000
	buffer_load_dwordx4 v[196:199], v208, s[40:43], s16 offen
	s_add_i32 s16, s14, 0x20e04000
	buffer_load_dwordx4 v[200:203], v208, s[40:43], s16 offen
	s_add_i32 s16, s14, 0x20e06000
	buffer_load_dwordx4 v[204:207], v208, s[40:43], s16 offen
	s_nop 7
	ds_read_b128 v[210:213], v247 offset:32768
	ds_read_b128 v[224:227], v247 offset:33280
	ds_read_b128 v[228:231], v247 offset:33792
	ds_read_b128 v[96:99], v248 offset:2560
	ds_read_b128 v[108:111], v248 offset:2624
	s_waitcnt lgkmcnt(4)
	v_mfma_f32_16x16x32_bf16 v[32:35], v[210:213], v[84:87], 0
	ds_read_b128 v[210:213], v247 offset:34304
	s_waitcnt lgkmcnt(4)
	v_mfma_f32_16x16x32_bf16 v[32:35], v[224:227], v[64:67], v[32:35]
	ds_read_b128 v[224:227], v247 offset:36864
	s_waitcnt lgkmcnt(4)
	v_mfma_f32_16x16x32_bf16 v[32:35], v[228:231], v[68:71], v[32:35]
	ds_read_b128 v[228:231], v247 offset:37376
	s_waitcnt lgkmcnt(2)
	v_mfma_f32_16x16x32_bf16 v[92:95], v[210:213], v[104:107], v[32:35]
	ds_read_b128 v[210:213], v247 offset:37888
	s_waitcnt lgkmcnt(2)
	v_mfma_f32_16x16x32_bf16 v[32:35], v[224:227], v[84:87], 0
	ds_read_b128 v[224:227], v247 offset:38400
	s_waitcnt lgkmcnt(2)
	v_mfma_f32_16x16x32_bf16 v[32:35], v[228:231], v[64:67], v[32:35]
	s_waitcnt lgkmcnt(1)
	v_mfma_f32_16x16x32_bf16 v[32:35], v[210:213], v[68:71], v[32:35]
	s_waitcnt lgkmcnt(0)
	v_mfma_f32_16x16x32_bf16 v[100:103], v[224:227], v[104:107], v[32:35]
	s_nop 7
	s_nop 0
	s_add_i32 s16, s14, 0x20e20000
	s_waitcnt vmcnt(11)
	ds_write_b128 v249, v[36:39]
	s_waitcnt vmcnt(10)
	ds_write_b128 v249, v[44:47] offset:8192
	s_waitcnt vmcnt(9)
	ds_write_b128 v249, v[72:75] offset:16384
	s_waitcnt vmcnt(8)
	ds_write_b128 v249, v[76:79] offset:24576
	s_waitcnt lgkmcnt(0)
	s_barrier
	buffer_load_dwordx4 v[32:35], v208, s[40:43], s16 offen
	s_add_i32 s16, s14, 0x20e22000
	buffer_load_dwordx4 v[40:43], v208, s[40:43], s16 offen
	s_add_i32 s16, s14, 0x20e24000
	buffer_load_dwordx4 v[44:47], v208, s[40:43], s16 offen
	s_add_i32 s16, s14, 0x20e26000
	buffer_load_dwordx4 v[56:59], v208, s[40:43], s16 offen
	s_nop 7
	ds_read_b128 v[210:213], v247
	ds_read_b128 v[224:227], v247 offset:512
	ds_read_b128 v[228:231], v247 offset:1024
	ds_read_b128 v[76:79], v248 offset:3072
	ds_read_b128 v[88:91], v248 offset:3136
	s_waitcnt lgkmcnt(4)
	v_mfma_f32_16x16x32_bf16 v[36:39], v[210:213], v[84:87], 0
	ds_read_b128 v[210:213], v247 offset:1536
	s_waitcnt lgkmcnt(4)
	v_mfma_f32_16x16x32_bf16 v[36:39], v[224:227], v[64:67], v[36:39]
	ds_read_b128 v[224:227], v247 offset:4096
	s_waitcnt lgkmcnt(4)
	v_mfma_f32_16x16x32_bf16 v[36:39], v[228:231], v[68:71], v[36:39]
	ds_read_b128 v[228:231], v247 offset:4608
	s_waitcnt lgkmcnt(2)
	v_mfma_f32_16x16x32_bf16 v[72:75], v[210:213], v[104:107], v[36:39]
	ds_read_b128 v[210:213], v247 offset:5120
	s_waitcnt lgkmcnt(2)
	v_mfma_f32_16x16x32_bf16 v[36:39], v[224:227], v[84:87], 0
	ds_read_b128 v[224:227], v247 offset:5632
	s_waitcnt lgkmcnt(2)
	v_mfma_f32_16x16x32_bf16 v[36:39], v[228:231], v[64:67], v[36:39]
	s_waitcnt lgkmcnt(1)
	v_mfma_f32_16x16x32_bf16 v[36:39], v[210:213], v[68:71], v[36:39]
	s_waitcnt lgkmcnt(0)
	v_mfma_f32_16x16x32_bf16 v[80:83], v[224:227], v[104:107], v[36:39]
	s_nop 7
	s_nop 0
	s_add_i32 s16, s14, 0x20e40000
	s_waitcnt vmcnt(11)
	ds_write_b128 v249, v[48:51] offset:32768
	s_waitcnt vmcnt(10)
	ds_write_b128 v249, v[52:55] offset:40960
	s_waitcnt vmcnt(9)
	ds_write_b128 v249, v[140:143] offset:49152
	s_waitcnt vmcnt(8)
	ds_write_b128 v249, v[192:195] offset:57344
	s_waitcnt lgkmcnt(0)
	s_barrier
	buffer_load_dwordx4 v[36:39], v208, s[40:43], s16 offen
	s_add_i32 s16, s14, 0x20e42000
	buffer_load_dwordx4 v[48:51], v208, s[40:43], s16 offen
	s_add_i32 s16, s14, 0x20e44000
	buffer_load_dwordx4 v[52:55], v208, s[40:43], s16 offen
	s_add_i32 s16, s14, 0x20e46000
	buffer_load_dwordx4 v[60:63], v208, s[40:43], s16 offen
	s_nop 7
	ds_read_b128 v[210:213], v247 offset:32768
	ds_read_b128 v[224:227], v247 offset:36864
	ds_read_b128 v[228:231], v247 offset:33280
	s_waitcnt lgkmcnt(2)
	v_mfma_f32_16x16x32_bf16 v[140:143], v[210:213], v[84:87], 0
	ds_read_b128 v[210:213], v247 offset:33792
	s_waitcnt lgkmcnt(2)
	v_mfma_f32_16x16x32_bf16 v[192:195], v[224:227], v[84:87], 0
	ds_read_b128 v[224:227], v247 offset:34304
	s_waitcnt lgkmcnt(2)
	v_mfma_f32_16x16x32_bf16 v[84:87], v[228:231], v[64:67], v[140:143]
	ds_read_b128 v[228:231], v247 offset:37376
	s_nop 0
	ds_read_b128 v[140:143], v248 offset:3584
	s_waitcnt lgkmcnt(3)
	v_mfma_f32_16x16x32_bf16 v[84:87], v[210:213], v[68:71], v[84:87]
	ds_read_b128 v[210:213], v247 offset:37888
	s_waitcnt lgkmcnt(3)
	v_mfma_f32_16x16x32_bf16 v[84:87], v[224:227], v[104:107], v[84:87]
	ds_read_b128 v[224:227], v247 offset:38400
	s_waitcnt lgkmcnt(3)
	v_mfma_f32_16x16x32_bf16 v[64:67], v[228:231], v[64:67], v[192:195]
	s_waitcnt lgkmcnt(1)
	v_mfma_f32_16x16x32_bf16 v[68:71], v[210:213], v[68:71], v[64:67]
	s_nop 5
	ds_read_b128 v[64:67], v248 offset:3648
	s_waitcnt lgkmcnt(1)
	v_mfma_f32_16x16x32_bf16 v[68:71], v[224:227], v[104:107], v[68:71]
	s_waitcnt lgkmcnt(0)
	s_nop 6
	s_nop 0
	s_mul_i32 s3, s3, 15
	s_sub_i32 s16, s3, s2
	s_add_i32 s16, s16, 7
	s_add_i32 s15, s16, s15
	s_mul_i32 s15, s15, 31
	s_waitcnt vmcnt(11)
	ds_write_b128 v249, v[188:191]
	s_waitcnt vmcnt(10)
	ds_write_b128 v249, v[196:199] offset:8192
	s_waitcnt vmcnt(9)
	ds_write_b128 v249, v[200:203] offset:16384
	s_waitcnt vmcnt(8)
	ds_write_b128 v249, v[204:207] offset:24576
	s_add_i32 s17, s15, 15
	v_mov_b32_e32 v188, 0xf149f2ca
	v_mov_b32_e32 v189, 0xf149f2ca
	s_waitcnt lgkmcnt(0)
	s_barrier
; #define LAS __attribute__((address_space(3)))
; __device__ __forceinline__ void na_attn_block(LAS unsigned char* lds, rsrc_t R, int l, int bx, int G, int tid, int lane, int wave) {
;     ...
;         { const int rowidx0 = start - r + 7;
; #pragma unroll
;           for (int a = 0; a < 8; ++a)
; #pragma unroll
;               for (int q = 0; q < 8; ++q) { const int kcol = kc0 + 16 * (q >> 2) + 4 * kq + (q & 3); const bool valid = (kcol >= cs) && (kcol < cs + 16);
;                   int ci = kcol - qcol + 15; ci = ci < 0 ? 0 : (ci > 30 ? 30 : ci);
;                   const float bias = *(const LAS float*)(lds + NA_RPB + ((h * 15 + rowidx0 + a) * 31 + ci) * 4);
;                   S[a][q >> 2][q & 3] = valid ? S[a][q >> 2][q & 3] + bias : -1e30f; } }
	v_add_u32_e32 v210, s17, v238
	v_lshl_add_u32 v210, v210, 2, 0
	v_add_u32_e32 v210, 0x11000, v210
	ds_read_b32 v210, v210
	v_add_u32_e32 v211, s17, v239
	v_lshl_add_u32 v211, v211, 2, 0
	v_add_u32_e32 v211, 0x11000, v211
	ds_read_b32 v211, v211
	v_add_u32_e32 v212, s17, v240
	v_lshl_add_u32 v212, v212, 2, 0
	v_add_u32_e32 v212, 0x11000, v212
	ds_read_b32 v212, v212
	v_add_u32_e32 v213, s17, v241
	v_lshl_add_u32 v213, v213, 2, 0
	v_add_u32_e32 v213, 0x11000, v213
	ds_read_b32 v213, v213
	s_waitcnt lgkmcnt(3)
	v_add_f32_e32 v210, v216, v210
	v_cndmask_b32_e64 v189, v189, v210, s[6:7]
	s_waitcnt lgkmcnt(2)
	v_add_f32_e32 v211, v217, v211
	v_cndmask_b32_e64 v188, v188, v211, s[22:23]
	v_mov_b32_e32 v190, 0xf149f2ca
	v_mov_b32_e32 v191, 0xf149f2ca
	s_waitcnt lgkmcnt(1)
	v_add_f32_e32 v212, v214, v212
	v_cndmask_b32_e64 v191, v191, v212, s[28:29]
	s_waitcnt lgkmcnt(0)
	v_add_f32_e32 v213, v215, v213
	v_cndmask_b32_e64 v190, v190, v213, s[30:31]
	v_pk_mul_f32 v[104:105], v[178:179], v[186:187]
	v_pk_mul_f32 v[106:107], v[176:177], v[184:185]
	v_mov_b32_e32 v176, 0xf149f2ca
	v_mov_b32_e32 v177, 0xf149f2ca
	v_add_u32_e32 v210, s17, v242
	v_lshl_add_u32 v210, v210, 2, 0
	v_add_u32_e32 v210, 0x11000, v210
	ds_read_b32 v210, v210
	v_add_u32_e32 v211, s17, v243
	v_lshl_add_u32 v211, v211, 2, 0
	v_add_u32_e32 v211, 0x11000, v211
	ds_read_b32 v211, v211
	v_add_u32_e32 v212, s17, v244
	v_lshl_add_u32 v212, v212, 2, 0
	v_add_u32_e32 v212, 0x11000, v212
	ds_read_b32 v212, v212
	v_add_u32_e32 v213, s17, v245
	v_lshl_add_u32 v213, v213, 2, 0
	v_add_u32_e32 v213, 0x11000, v213
	ds_read_b32 v213, v213
	s_waitcnt lgkmcnt(3)
	v_add_f32_e32 v210, v106, v210
	v_cndmask_b32_e64 v177, v177, v210, s[36:37]
	s_waitcnt lgkmcnt(2)
	v_add_f32_e32 v211, v107, v211
	v_cndmask_b32_e64 v176, v176, v211, s[38:39]
	v_mov_b32_e32 v178, 0xf149f2ca
	v_mov_b32_e32 v179, 0xf149f2ca
	s_waitcnt lgkmcnt(1)
	v_add_f32_e32 v212, v104, v212
	v_cndmask_b32_e64 v179, v179, v212, s[44:45]
	s_waitcnt lgkmcnt(0)
	v_add_f32_e32 v213, v105, v213
	v_cndmask_b32_e64 v178, v178, v213, s[0:1]
	v_pk_mul_f32 v[104:105], v[166:167], v[170:171]
	v_pk_mul_f32 v[106:107], v[164:165], v[168:169]
	s_add_i32 s17, s15, 46
	v_mov_b32_e32 v164, 0xf149f2ca
	v_mov_b32_e32 v165, 0xf149f2ca
	v_add_u32_e32 v210, s17, v238
	v_lshl_add_u32 v210, v210, 2, 0
	v_add_u32_e32 v210, 0x11000, v210
	ds_read_b32 v210, v210
	v_add_u32_e32 v211, s17, v239
	v_lshl_add_u32 v211, v211, 2, 0
	v_add_u32_e32 v211, 0x11000, v211
	ds_read_b32 v211, v211
	v_add_u32_e32 v212, s17, v240
	v_lshl_add_u32 v212, v212, 2, 0
	v_add_u32_e32 v212, 0x11000, v212
	ds_read_b32 v212, v212
	v_add_u32_e32 v213, s17, v241
	v_lshl_add_u32 v213, v213, 2, 0
	v_add_u32_e32 v213, 0x11000, v213
	ds_read_b32 v213, v213
	s_waitcnt lgkmcnt(3)
	v_add_f32_e32 v210, v106, v210
	v_cndmask_b32_e64 v165, v165, v210, s[6:7]
	s_waitcnt lgkmcnt(2)
	v_add_f32_e32 v211, v107, v211
	v_cndmask_b32_e64 v164, v164, v211, s[22:23]
	v_mov_b32_e32 v166, 0xf149f2ca
	v_mov_b32_e32 v167, 0xf149f2ca
	s_waitcnt lgkmcnt(1)
	v_add_f32_e32 v212, v104, v212
	v_cndmask_b32_e64 v167, v167, v212, s[28:29]
	s_waitcnt lgkmcnt(0)
	v_add_f32_e32 v213, v105, v213
	v_cndmask_b32_e64 v166, v166, v213, s[30:31]
	v_pk_mul_f32 v[104:105], v[174:175], v[182:183]
	v_pk_mul_f32 v[106:107], v[172:173], v[180:181]
	v_mov_b32_e32 v168, 0xf149f2ca
	v_mov_b32_e32 v169, 0xf149f2ca
	v_add_u32_e32 v210, s17, v242
	v_lshl_add_u32 v210, v210, 2, 0
	v_add_u32_e32 v210, 0x11000, v210
	ds_read_b32 v210, v210
	v_add_u32_e32 v211, s17, v243
	v_lshl_add_u32 v211, v211, 2, 0
	v_add_u32_e32 v211, 0x11000, v211
	ds_read_b32 v211, v211
	v_add_u32_e32 v212, s17, v244
	v_lshl_add_u32 v212, v212, 2, 0
	v_add_u32_e32 v212, 0x11000, v212
	ds_read_b32 v212, v212
	v_add_u32_e32 v213, s17, v245
	v_lshl_add_u32 v213, v213, 2, 0
	v_add_u32_e32 v213, 0x11000, v213
	ds_read_b32 v213, v213
	s_waitcnt lgkmcnt(3)
	v_add_f32_e32 v210, v106, v210
	v_cndmask_b32_e64 v169, v169, v210, s[36:37]
	s_waitcnt lgkmcnt(2)
	v_add_f32_e32 v211, v107, v211
	v_cndmask_b32_e64 v168, v168, v211, s[38:39]
	v_mov_b32_e32 v170, 0xf149f2ca
	v_mov_b32_e32 v171, 0xf149f2ca
	s_waitcnt lgkmcnt(1)
	v_add_f32_e32 v212, v104, v212
	v_cndmask_b32_e64 v171, v171, v212, s[44:45]
	s_waitcnt lgkmcnt(0)
	v_add_f32_e32 v213, v105, v213
	v_cndmask_b32_e64 v170, v170, v213, s[0:1]
	v_pk_mul_f32 v[104:105], v[150:151], v[154:155]
	v_pk_mul_f32 v[106:107], v[148:149], v[152:153]
	s_add_i32 s17, s15, 0x4d
	v_mov_b32_e32 v148, 0xf149f2ca
	v_mov_b32_e32 v149, 0xf149f2ca
	v_add_u32_e32 v210, s17, v238
	v_lshl_add_u32 v210, v210, 2, 0
	v_add_u32_e32 v210, 0x11000, v210
	ds_read_b32 v210, v210
	v_add_u32_e32 v211, s17, v239
	v_lshl_add_u32 v211, v211, 2, 0
	v_add_u32_e32 v211, 0x11000, v211
	ds_read_b32 v211, v211
	v_add_u32_e32 v212, s17, v240
	v_lshl_add_u32 v212, v212, 2, 0
	v_add_u32_e32 v212, 0x11000, v212
	ds_read_b32 v212, v212
	v_add_u32_e32 v213, s17, v241
	v_lshl_add_u32 v213, v213, 2, 0
	v_add_u32_e32 v213, 0x11000, v213
	ds_read_b32 v213, v213
	s_waitcnt lgkmcnt(3)
	v_add_f32_e32 v210, v106, v210
	v_cndmask_b32_e64 v149, v149, v210, s[6:7]
	s_waitcnt lgkmcnt(2)
	v_add_f32_e32 v211, v107, v211
	v_cndmask_b32_e64 v148, v148, v211, s[22:23]
	v_mov_b32_e32 v150, 0xf149f2ca
	v_mov_b32_e32 v151, 0xf149f2ca
	s_waitcnt lgkmcnt(1)
	v_add_f32_e32 v212, v104, v212
	v_cndmask_b32_e64 v151, v151, v212, s[28:29]
	s_waitcnt lgkmcnt(0)
; #define LAS __attribute__((address_space(3)))
; __device__ __forceinline__ void na_attn_block(LAS unsigned char* lds, rsrc_t R, int l, int bx, int G, int tid, int lane, int wave) {
;     ...
;         { const int rowidx0 = start - r + 7;
; #pragma unroll
;           for (int a = 0; a < 8; ++a)
; #pragma unroll
;               for (int q = 0; q < 8; ++q) { const int kcol = kc0 + 16 * (q >> 2) + 4 * kq + (q & 3); const bool valid = (kcol >= cs) && (kcol < cs + 16);
;                   int ci = kcol - qcol + 15; ci = ci < 0 ? 0 : (ci > 30 ? 30 : ci);
;                   const float bias = *(const LAS float*)(lds + NA_RPB + ((h * 15 + rowidx0 + a) * 31 + ci) * 4);
;                   S[a][q >> 2][q & 3] = valid ? S[a][q >> 2][q & 3] + bias : -1e30f; } }
	v_add_f32_e32 v213, v105, v213
	v_cndmask_b32_e64 v150, v150, v213, s[30:31]
	v_pk_mul_f32 v[104:105], v[158:159], v[162:163]
	v_pk_mul_f32 v[106:107], v[156:157], v[160:161]
	v_mov_b32_e32 v152, 0xf149f2ca
	v_mov_b32_e32 v153, 0xf149f2ca
	v_add_u32_e32 v210, s17, v242
	v_lshl_add_u32 v210, v210, 2, 0
	v_add_u32_e32 v210, 0x11000, v210
	ds_read_b32 v210, v210
	v_add_u32_e32 v211, s17, v243
	v_lshl_add_u32 v211, v211, 2, 0
	v_add_u32_e32 v211, 0x11000, v211
	ds_read_b32 v211, v211
	v_add_u32_e32 v212, s17, v244
	v_lshl_add_u32 v212, v212, 2, 0
	v_add_u32_e32 v212, 0x11000, v212
	ds_read_b32 v212, v212
	v_add_u32_e32 v213, s17, v245
	v_lshl_add_u32 v213, v213, 2, 0
	v_add_u32_e32 v213, 0x11000, v213
	ds_read_b32 v213, v213
	s_waitcnt lgkmcnt(3)
	v_add_f32_e32 v210, v106, v210
	v_cndmask_b32_e64 v153, v153, v210, s[36:37]
	s_waitcnt lgkmcnt(2)
	v_add_f32_e32 v211, v107, v211
	v_cndmask_b32_e64 v152, v152, v211, s[38:39]
	v_mov_b32_e32 v154, 0xf149f2ca
	v_mov_b32_e32 v155, 0xf149f2ca
	s_waitcnt lgkmcnt(1)
	v_add_f32_e32 v212, v104, v212
	v_cndmask_b32_e64 v155, v155, v212, s[44:45]
	s_waitcnt lgkmcnt(0)
	v_add_f32_e32 v213, v105, v213
	v_cndmask_b32_e64 v154, v154, v213, s[0:1]
	v_pk_mul_f32 v[104:105], v[130:131], v[134:135]
	v_pk_mul_f32 v[106:107], v[128:129], v[132:133]
	s_add_i32 s17, s15, 0x6c
	v_mov_b32_e32 v128, 0xf149f2ca
	v_mov_b32_e32 v129, 0xf149f2ca
	v_add_u32_e32 v210, s17, v238
	v_lshl_add_u32 v210, v210, 2, 0
	v_add_u32_e32 v210, 0x11000, v210
	ds_read_b32 v210, v210
	v_add_u32_e32 v211, s17, v239
	v_lshl_add_u32 v211, v211, 2, 0
	v_add_u32_e32 v211, 0x11000, v211
	ds_read_b32 v211, v211
	v_add_u32_e32 v212, s17, v240
	v_lshl_add_u32 v212, v212, 2, 0
	v_add_u32_e32 v212, 0x11000, v212
	ds_read_b32 v212, v212
	v_add_u32_e32 v213, s17, v241
	v_lshl_add_u32 v213, v213, 2, 0
	v_add_u32_e32 v213, 0x11000, v213
	ds_read_b32 v213, v213
	s_waitcnt lgkmcnt(3)
	v_add_f32_e32 v210, v106, v210
	v_cndmask_b32_e64 v129, v129, v210, s[6:7]
	s_waitcnt lgkmcnt(2)
	v_add_f32_e32 v211, v107, v211
	v_cndmask_b32_e64 v128, v128, v211, s[22:23]
	v_mov_b32_e32 v130, 0xf149f2ca
	v_mov_b32_e32 v131, 0xf149f2ca
	s_waitcnt lgkmcnt(1)
	v_add_f32_e32 v212, v104, v212
	v_cndmask_b32_e64 v131, v131, v212, s[28:29]
	s_waitcnt lgkmcnt(0)
	v_add_f32_e32 v213, v105, v213
	v_cndmask_b32_e64 v130, v130, v213, s[30:31]
	v_pk_mul_f32 v[104:105], v[138:139], v[146:147]
	v_pk_mul_f32 v[106:107], v[136:137], v[144:145]
	v_mov_b32_e32 v132, 0xf149f2ca
	v_mov_b32_e32 v133, 0xf149f2ca
	v_add_u32_e32 v210, s17, v242
	v_lshl_add_u32 v210, v210, 2, 0
	v_add_u32_e32 v210, 0x11000, v210
	ds_read_b32 v210, v210
	v_add_u32_e32 v211, s17, v243
	v_lshl_add_u32 v211, v211, 2, 0
	v_add_u32_e32 v211, 0x11000, v211
	ds_read_b32 v211, v211
	v_add_u32_e32 v212, s17, v244
	v_lshl_add_u32 v212, v212, 2, 0
	v_add_u32_e32 v212, 0x11000, v212
	ds_read_b32 v212, v212
	v_add_u32_e32 v213, s17, v245
	v_lshl_add_u32 v213, v213, 2, 0
	v_add_u32_e32 v213, 0x11000, v213
	ds_read_b32 v213, v213
	s_waitcnt lgkmcnt(3)
	v_add_f32_e32 v210, v106, v210
	v_cndmask_b32_e64 v133, v133, v210, s[36:37]
	s_waitcnt lgkmcnt(2)
	v_add_f32_e32 v211, v107, v211
	v_cndmask_b32_e64 v132, v132, v211, s[38:39]
	v_mov_b32_e32 v134, 0xf149f2ca
	v_mov_b32_e32 v135, 0xf149f2ca
	s_waitcnt lgkmcnt(1)
	v_add_f32_e32 v212, v104, v212
	v_cndmask_b32_e64 v135, v135, v212, s[44:45]
	s_waitcnt lgkmcnt(0)
	v_add_f32_e32 v213, v105, v213
	v_cndmask_b32_e64 v134, v134, v213, s[0:1]
	v_pk_mul_f32 v[106:107], v[116:117], v[120:121]
	v_add_u32_e32 v116, s16, v250
	v_mul_lo_u32 v116, v116, 31
	v_pk_mul_f32 v[104:105], v[118:119], v[122:123]
	v_add_u32_e32 v120, 15, v116
	v_mov_b32_e32 v116, 0xf149f2ca
	v_mov_b32_e32 v117, 0xf149f2ca
	v_add_u32_e32 v210, v120, v238
	v_lshl_add_u32 v210, v210, 2, 0
	v_add_u32_e32 v210, 0x11000, v210
	ds_read_b32 v210, v210
	v_add_u32_e32 v211, v120, v239
	v_lshl_add_u32 v211, v211, 2, 0
	v_add_u32_e32 v211, 0x11000, v211
	ds_read_b32 v211, v211
	v_add_u32_e32 v212, v120, v240
	v_lshl_add_u32 v212, v212, 2, 0
	v_add_u32_e32 v212, 0x11000, v212
	ds_read_b32 v212, v212
	v_add_u32_e32 v213, v120, v241
	v_lshl_add_u32 v213, v213, 2, 0
	v_add_u32_e32 v213, 0x11000, v213
	ds_read_b32 v213, v213
	s_waitcnt lgkmcnt(3)
	v_add_f32_e32 v210, v106, v210
	v_cndmask_b32_e64 v117, v117, v210, s[6:7]
	s_waitcnt lgkmcnt(2)
	v_add_f32_e32 v211, v107, v211
	v_cndmask_b32_e64 v116, v116, v211, s[22:23]
	v_mov_b32_e32 v118, 0xf149f2ca
	v_mov_b32_e32 v119, 0xf149f2ca
	s_waitcnt lgkmcnt(1)
	v_add_f32_e32 v212, v104, v212
	v_cndmask_b32_e64 v119, v119, v212, s[28:29]
	s_waitcnt lgkmcnt(0)
	v_add_f32_e32 v213, v105, v213
	v_cndmask_b32_e64 v118, v118, v213, s[30:31]
	v_pk_mul_f32 v[104:105], v[114:115], v[126:127]
	v_pk_mul_f32 v[106:107], v[112:113], v[124:125]
	v_mov_b32_e32 v112, 0xf149f2ca
	v_mov_b32_e32 v113, 0xf149f2ca
	v_add_u32_e32 v210, v120, v242
	v_lshl_add_u32 v210, v210, 2, 0
	v_add_u32_e32 v210, 0x11000, v210
	ds_read_b32 v210, v210
	v_add_u32_e32 v211, v120, v243
	v_lshl_add_u32 v211, v211, 2, 0
	v_add_u32_e32 v211, 0x11000, v211
	ds_read_b32 v211, v211
	v_add_u32_e32 v212, v120, v244
	v_lshl_add_u32 v212, v212, 2, 0
	v_add_u32_e32 v212, 0x11000, v212
	ds_read_b32 v212, v212
	v_add_u32_e32 v213, v120, v245
	v_lshl_add_u32 v213, v213, 2, 0
	v_add_u32_e32 v213, 0x11000, v213
	ds_read_b32 v213, v213
	s_waitcnt lgkmcnt(3)
	v_add_f32_e32 v210, v106, v210
	v_cndmask_b32_e64 v113, v113, v210, s[36:37]
	s_waitcnt lgkmcnt(2)
	v_add_f32_e32 v211, v107, v211
	v_cndmask_b32_e64 v112, v112, v211, s[38:39]
	v_mov_b32_e32 v106, 0xf149f2ca
	v_mov_b32_e32 v107, 0xf149f2ca
	s_waitcnt lgkmcnt(1)
; #define LAS __attribute__((address_space(3)))
; __device__ __forceinline__ void na_attn_block(LAS unsigned char* lds, rsrc_t R, int l, int bx, int G, int tid, int lane, int wave) {
;     ...
;         { const int rowidx0 = start - r + 7;
; #pragma unroll
;           for (int a = 0; a < 8; ++a)
; #pragma unroll
;               for (int q = 0; q < 8; ++q) { const int kcol = kc0 + 16 * (q >> 2) + 4 * kq + (q & 3); const bool valid = (kcol >= cs) && (kcol < cs + 16);
;                   int ci = kcol - qcol + 15; ci = ci < 0 ? 0 : (ci > 30 ? 30 : ci);
;                   const float bias = *(const LAS float*)(lds + NA_RPB + ((h * 15 + rowidx0 + a) * 31 + ci) * 4);
;                   S[a][q >> 2][q & 3] = valid ? S[a][q >> 2][q & 3] + bias : -1e30f; } }
	v_add_f32_e32 v212, v104, v212
	v_cndmask_b32_e64 v107, v107, v212, s[44:45]
	s_waitcnt lgkmcnt(0)
	v_add_f32_e32 v213, v105, v213
	v_cndmask_b32_e64 v106, v106, v213, s[0:1]
	v_pk_mul_f32 v[94:95], v[94:95], v[98:99]
	v_pk_mul_f32 v[92:93], v[92:93], v[96:97]
	s_add_i32 s16, s15, 0xaa
	v_mov_b32_e32 v96, 0xf149f2ca
	v_mov_b32_e32 v97, 0xf149f2ca
	v_add_u32_e32 v210, s16, v238
	v_lshl_add_u32 v210, v210, 2, 0
	v_add_u32_e32 v210, 0x11000, v210
	ds_read_b32 v210, v210
	v_add_u32_e32 v211, s16, v239
	v_lshl_add_u32 v211, v211, 2, 0
	v_add_u32_e32 v211, 0x11000, v211
	ds_read_b32 v211, v211
	v_add_u32_e32 v212, s16, v240
	v_lshl_add_u32 v212, v212, 2, 0
	v_add_u32_e32 v212, 0x11000, v212
	ds_read_b32 v212, v212
	v_add_u32_e32 v213, s16, v241
	v_lshl_add_u32 v213, v213, 2, 0
	v_add_u32_e32 v213, 0x11000, v213
	ds_read_b32 v213, v213
	s_waitcnt lgkmcnt(3)
	v_add_f32_e32 v210, v92, v210
	v_cndmask_b32_e64 v97, v97, v210, s[6:7]
	s_waitcnt lgkmcnt(2)
	v_add_f32_e32 v211, v93, v211
	v_cndmask_b32_e64 v96, v96, v211, s[22:23]
	v_mov_b32_e32 v98, 0xf149f2ca
	v_mov_b32_e32 v99, 0xf149f2ca
	s_waitcnt lgkmcnt(1)
	v_add_f32_e32 v212, v94, v212
	v_cndmask_b32_e64 v99, v99, v212, s[28:29]
	s_waitcnt lgkmcnt(0)
	v_add_f32_e32 v213, v95, v213
	v_cndmask_b32_e64 v98, v98, v213, s[30:31]
	v_pk_mul_f32 v[92:93], v[102:103], v[110:111]
	v_pk_mul_f32 v[94:95], v[100:101], v[108:109]
	v_mov_b32_e32 v100, 0xf149f2ca
	v_mov_b32_e32 v105, 0xf149f2ca
	v_add_u32_e32 v210, s16, v242
	v_lshl_add_u32 v210, v210, 2, 0
	v_add_u32_e32 v210, 0x11000, v210
	ds_read_b32 v210, v210
	v_add_u32_e32 v211, s16, v243
	v_lshl_add_u32 v211, v211, 2, 0
	v_add_u32_e32 v211, 0x11000, v211
	ds_read_b32 v211, v211
	v_add_u32_e32 v212, s16, v244
	v_lshl_add_u32 v212, v212, 2, 0
	v_add_u32_e32 v212, 0x11000, v212
	ds_read_b32 v212, v212
	v_add_u32_e32 v213, s16, v245
	v_lshl_add_u32 v213, v213, 2, 0
	v_add_u32_e32 v213, 0x11000, v213
	ds_read_b32 v213, v213
	s_waitcnt lgkmcnt(3)
	v_add_f32_e32 v210, v94, v210
	v_cndmask_b32_e64 v105, v105, v210, s[36:37]
	s_waitcnt lgkmcnt(2)
	v_add_f32_e32 v211, v95, v211
	v_cndmask_b32_e64 v100, v100, v211, s[38:39]
	v_mov_b32_e32 v94, 0xf149f2ca
	v_mov_b32_e32 v95, 0xf149f2ca
	s_waitcnt lgkmcnt(1)
	v_add_f32_e32 v212, v92, v212
	v_cndmask_b32_e64 v95, v95, v212, s[44:45]
	s_waitcnt lgkmcnt(0)
	v_add_f32_e32 v213, v93, v213
	v_cndmask_b32_e64 v94, v94, v213, s[0:1]
	v_pk_mul_f32 v[74:75], v[74:75], v[78:79]
	v_pk_mul_f32 v[72:73], v[72:73], v[76:77]
	s_add_i32 s16, s15, 0xc9
	v_mov_b32_e32 v76, 0xf149f2ca
	v_mov_b32_e32 v77, 0xf149f2ca
	v_add_u32_e32 v210, s16, v238
	v_lshl_add_u32 v210, v210, 2, 0
	v_add_u32_e32 v210, 0x11000, v210
	ds_read_b32 v210, v210
	v_add_u32_e32 v211, s16, v239
	v_lshl_add_u32 v211, v211, 2, 0
	v_add_u32_e32 v211, 0x11000, v211
	ds_read_b32 v211, v211
	v_add_u32_e32 v212, s16, v240
	v_lshl_add_u32 v212, v212, 2, 0
	v_add_u32_e32 v212, 0x11000, v212
	ds_read_b32 v212, v212
	v_add_u32_e32 v213, s16, v241
	v_lshl_add_u32 v213, v213, 2, 0
	v_add_u32_e32 v213, 0x11000, v213
	ds_read_b32 v213, v213
	s_waitcnt lgkmcnt(3)
	v_add_f32_e32 v210, v72, v210
	v_cndmask_b32_e64 v77, v77, v210, s[6:7]
	s_waitcnt lgkmcnt(2)
	v_add_f32_e32 v211, v73, v211
	v_cndmask_b32_e64 v76, v76, v211, s[22:23]
	v_mov_b32_e32 v78, 0xf149f2ca
	v_mov_b32_e32 v79, 0xf149f2ca
	s_waitcnt lgkmcnt(1)
	v_add_f32_e32 v212, v74, v212
	v_cndmask_b32_e64 v79, v79, v212, s[28:29]
	s_waitcnt lgkmcnt(0)
	v_add_f32_e32 v213, v75, v213
	v_cndmask_b32_e64 v78, v78, v213, s[30:31]
	v_pk_mul_f32 v[72:73], v[82:83], v[90:91]
	v_pk_mul_f32 v[74:75], v[80:81], v[88:89]
	v_mov_b32_e32 v80, 0xf149f2ca
	v_mov_b32_e32 v81, 0xf149f2ca
	v_add_u32_e32 v210, s16, v242
	v_lshl_add_u32 v210, v210, 2, 0
	v_add_u32_e32 v210, 0x11000, v210
	ds_read_b32 v210, v210
	v_add_u32_e32 v211, s16, v243
	v_lshl_add_u32 v211, v211, 2, 0
	v_add_u32_e32 v211, 0x11000, v211
	ds_read_b32 v211, v211
	v_add_u32_e32 v212, s16, v244
	v_lshl_add_u32 v212, v212, 2, 0
	v_add_u32_e32 v212, 0x11000, v212
	ds_read_b32 v212, v212
	v_add_u32_e32 v213, s16, v245
	v_lshl_add_u32 v213, v213, 2, 0
	v_add_u32_e32 v213, 0x11000, v213
	ds_read_b32 v213, v213
	s_waitcnt lgkmcnt(3)
	v_add_f32_e32 v210, v74, v210
	v_cndmask_b32_e64 v81, v81, v210, s[36:37]
	s_waitcnt lgkmcnt(2)
	v_add_f32_e32 v211, v75, v211
	v_cndmask_b32_e64 v80, v80, v211, s[38:39]
	v_mov_b32_e32 v82, 0xf149f2ca
	v_mov_b32_e32 v83, 0xf149f2ca
	s_waitcnt lgkmcnt(1)
	v_add_f32_e32 v212, v72, v212
	v_cndmask_b32_e64 v83, v83, v212, s[44:45]
	s_waitcnt lgkmcnt(0)
	v_add_f32_e32 v213, v73, v213
	v_cndmask_b32_e64 v82, v82, v213, s[0:1]
	v_pk_mul_f32 v[72:73], v[86:87], v[142:143]
	v_pk_mul_f32 v[74:75], v[84:85], v[140:141]
	s_addk_i32 s15, 0xe8
	v_mov_b32_e32 v84, 0xf149f2ca
	v_mov_b32_e32 v85, 0xf149f2ca
	v_add_u32_e32 v210, s15, v238
	v_lshl_add_u32 v210, v210, 2, 0
	v_add_u32_e32 v210, 0x11000, v210
	ds_read_b32 v210, v210
	v_add_u32_e32 v211, s15, v239
	v_lshl_add_u32 v211, v211, 2, 0
	v_add_u32_e32 v211, 0x11000, v211
	ds_read_b32 v211, v211
	v_add_u32_e32 v212, s15, v240
	v_lshl_add_u32 v212, v212, 2, 0
	v_add_u32_e32 v212, 0x11000, v212
	ds_read_b32 v212, v212
	v_add_u32_e32 v213, s15, v241
	v_lshl_add_u32 v213, v213, 2, 0
	v_add_u32_e32 v213, 0x11000, v213
	ds_read_b32 v213, v213
	s_waitcnt lgkmcnt(3)
	v_add_f32_e32 v210, v74, v210
	v_cndmask_b32_e64 v85, v85, v210, s[6:7]
	s_waitcnt lgkmcnt(2)
	v_add_f32_e32 v211, v75, v211
	v_cndmask_b32_e64 v84, v84, v211, s[22:23]
	v_mov_b32_e32 v74, 0xf149f2ca
	v_mov_b32_e32 v75, 0xf149f2ca
	s_waitcnt lgkmcnt(1)
	v_add_f32_e32 v212, v72, v212
	v_cndmask_b32_e64 v75, v75, v212, s[28:29]
	s_waitcnt lgkmcnt(0)
	v_add_f32_e32 v213, v73, v213
	v_cndmask_b32_e64 v74, v74, v213, s[30:31]
	v_pk_mul_f32 v[66:67], v[70:71], v[66:67]
	v_pk_mul_f32 v[64:65], v[68:69], v[64:65]
	v_mov_b32_e32 v68, 0xf149f2ca
	v_mov_b32_e32 v69, 0xf149f2ca
	v_add_u32_e32 v210, s15, v242
	v_lshl_add_u32 v210, v210, 2, 0
	v_add_u32_e32 v210, 0x11000, v210
	ds_read_b32 v210, v210
	v_add_u32_e32 v211, s15, v243
	v_lshl_add_u32 v211, v211, 2, 0
	v_add_u32_e32 v211, 0x11000, v211
	ds_read_b32 v211, v211
	v_add_u32_e32 v212, s15, v244
	v_lshl_add_u32 v212, v212, 2, 0
	v_add_u32_e32 v212, 0x11000, v212
	ds_read_b32 v212, v212
	v_add_u32_e32 v213, s15, v245
	v_lshl_add_u32 v213, v213, 2, 0
	v_add_u32_e32 v213, 0x11000, v213
	ds_read_b32 v213, v213
	s_waitcnt lgkmcnt(3)
	v_add_f32_e32 v210, v64, v210
	v_cndmask_b32_e64 v69, v69, v210, s[36:37]
	s_waitcnt lgkmcnt(2)
	v_add_f32_e32 v211, v65, v211
	v_cndmask_b32_e64 v68, v68, v211, s[38:39]
	v_mov_b32_e32 v64, 0xf149f2ca
	v_mov_b32_e32 v65, 0xf149f2ca
	s_waitcnt lgkmcnt(1)
	v_add_f32_e32 v212, v66, v212
	v_cndmask_b32_e64 v65, v65, v212, s[44:45]
	s_waitcnt lgkmcnt(0)
	v_add_f32_e32 v213, v67, v213
	v_cndmask_b32_e64 v64, v64, v213, s[0:1]
	s_branch .LBB0_184
; #define FRESH_TID(name) int name; asm volatile("v_mbcnt_lo_u32_b32 %0, -1, 0\n\tv_mbcnt_hi_u32_b32 %0, -1, %0" : "=v"(name)); name += wave * 64
; __global__ void __launch_bounds__(NWAVES * 64, 2) mega_fwd(Args args) {
;     ...
;     for (int ph = args.ph_lo; ph < args.ph_hi; ++ph) {
;         unsigned char* ws = args.ws; asm volatile("" : "+s"(ws));
;     ...
;         const int G = gridDim.x, bx = blockIdx.x, vcu = (G % 8 == 0) ? (bx % 8) * (G / 8) + bx / 8 : bx;
;         const int gw = vcu * NWAVES + wave, NGW = G * NWAVES;
;         float* ss = (float*)(ws + WS_SS);
;         bf16_t* xb = (bf16_t*)(ws + WS_XB); bf16_t* proj = (bf16_t*)(ws + WS_PROJ); bf16_t* VT = (bf16_t*)(ws + WS_VT); bf16_t* yb = (bf16_t*)(ws + WS_Y);
;         bf16_t* A2r = (bf16_t*)(ws + WS_A2); bf16_t* A2i = A2r + (size_t)16 * 64 * 128 * 128; bf16_t* hid = (bf16_t*)(ws + WS_H);
;         bf16_t* memb = (bf16_t*)(ws + WS_MEMB); bf16_t* Km = (bf16_t*)(ws + WS_KM); bf16_t* VmT = (bf16_t*)(ws + WS_VMT);
;         const bf16_t* T64 = (const bf16_t*)(ws + WS_TAB + TAB_T64); const bf16_t* T128 = (const bf16_t*)(ws + WS_TAB + TAB_T128); const bf16_t* MT = (const bf16_t*)(ws + WS_TAB + TAB_MT); const float* GQK = (const float*)(ws + WS_TAB + TAB_GQK);
;         if (ph < NPRO) { FRESH_TID(tid); prologue(args, ws, lds, tid, tid & 63, wave, vcu, G); }
.LBB0_313:
	v_mov_b64_e32 v[210:211], 0x400
	v_mov_b64_e32 v[212:213], 0x3ff
	v_mov_b32_e32 v224, 0x108
	v_mov_b32_e32 v225, 0x210
	v_mov_b32_e32 v226, 0x318
	v_mov_b32_e32 v227, 0x420
	v_mov_b32_e32 v228, 0x528
	v_mov_b32_e32 v229, 0x630
	v_mov_b32_e32 v230, 0x738
	v_mov_b32_e32 v231, 0x840
	s_mov_b64 s[0:1], 0
